# P3 chain rewrite + fused diff-attn loop + gla_out gain-load hoist + reuse of LDS gain tables + first K/V tile loads issued with the Q loads in diff/mem attention prologues
# baseline (speedup 1.0000x reference)
; #define LAS __attribute__((address_space(3)))
;     template <bool BG = false>
;     __device__ __forceinline__ void run(LAS unsigned char* lds, f32x16 (&O)[NCOMP][NBLK], BgConv* bg = nullptr) const {
;     ...
;         const float qscale = ((DH == 128) ? 0.08838834764831845f : 0.0625f) * LOG2E;
; #pragma unroll
;         for (int pass = 0; pass < NRB / 2; ++pass) {
;             u32x4 qr[4]; tile_load(qr, Q + (size_t)(64 * pass) * ldq, ldq, tid);
;             tile_store_norm<DH, NCOMP>(qr, kbuf, gq, qscale, tid);
;             __syncthreads();
;             if (rbA / 2 == pass) {
; #pragma unroll
;                 for (int s = 0; s < KS; ++s) qf[s] = *(const LAS bf16x8*)(kbuf + ((32 * (rbA & 1) + r) * NCOMP + compA) * KST + (16 * s + 8 * h) * 2);
;             }
;             __syncthreads();
;         }
;         u32x4 kreg[4], vreg[4];
;         tile_load(kreg, K, ldk, tid); tile_load(vreg, V, ldv, tid);
; __device__ __forceinline__ void mem_unit(Frame& F, int b, int hd, int qb) {
;     ...
;     AU u; u.Q = Z + (size_t)(b * SEQ + 128 * qb) * NZ + ZQ_MEM + hd * 256; u.ldq = NZ; u.K = KVM + (size_t)(b * NMEM) * 2048 + hd * 256; u.ldk = 2048;
.LBB0_671:
	s_or_b64 exec, exec, s[18:19]
	s_ashr_i32 s18, s33, 7
	s_lshl_b32 s19, s33, 7
	s_lshl_b32 s8, s18, 12
	s_and_b32 s19, s19, 0xf80
	s_or_b32 s36, s19, s8
	s_mul_i32 s19, s36, 0x3c00
	s_mul_hi_i32 s8, s36, 0x3c00
	s_add_u32 s19, s34, s19
	s_addc_u32 s21, s35, s8
	s_lshl_b32 s8, s33, 3
	s_and_b32 s8, s8, 0x300
	s_lshl_b32 s8, s8, 1
	s_add_u32 s19, s19, s8
	s_addc_u32 s21, s21, 0
	s_add_u32 s38, s19, 0x8003000
	v_ashrrev_i32_e32 v4, 3, v2
	v_lshlrev_b32_e32 v3, 3, v2
	s_addc_u32 s39, s21, 0
	v_and_b32_e32 v5, 56, v3
	v_mad_i64_i32 v[6:7], s[40:41], v4, s25, 0
	v_lshl_add_u64 v[6:7], v[6:7], 1, s[38:39]
	v_lshlrev_b32_e32 v162, 1, v5
	v_lshl_add_u64 v[6:7], v[6:7], 0, v[162:163]
	s_waitcnt lgkmcnt(0)
	s_barrier
	global_load_dwordx4 v[16:19], v[6:7], off offset:128
	global_load_dwordx4 v[20:23], v[6:7], off offset:256
	global_load_dwordx4 v[24:27], v[6:7], off
	global_load_dwordx4 v[30:33], v[6:7], off offset:384
	s_lshl_b32 s98, s18, 8
	s_ashr_i32 s99, s98, 31
	s_lshl_b64 s[98:99], s[98:99], 12
	s_add_u32 s98, s13, s98
	s_addc_u32 s99, s15, s99
	s_add_u32 s98, s98, s8
	s_addc_u32 s99, s99, 0
	v_mov_b32_e32 v228, v4
	v_ashrrev_i32_e32 v229, 31, v4
	v_lshlrev_b64 v[228:229], 12, v[228:229]
	v_lshl_add_u64 v[228:229], s[98:99], 0, v[228:229]
	v_lshl_add_u64 v[228:229], v[228:229], 0, v[162:163]
	global_load_dwordx4 v[212:215], v[228:229], off
	global_load_dwordx4 v[216:219], v[228:229], off offset:128
	global_load_dwordx4 v[220:223], v[228:229], off offset:256
	global_load_dwordx4 v[224:227], v[228:229], off offset:384
	v_cmp_lt_i32_e32 vcc, v195, v196
	v_and_b32_e32 v64, 7, v2
	v_or_b32_e32 v10, 16, v64
	v_cndmask_b32_e32 v5, v194, v195, vcc
	v_cmp_lt_i32_e32 vcc, v197, v196
	v_lshlrev_b32_e32 v14, 2, v5
	v_mul_lo_u32 v5, v4, s23
	v_cndmask_b32_e32 v8, v194, v197, vcc
	v_cmp_lt_i32_e32 vcc, v198, v196
	v_lshlrev_b32_e32 v13, 2, v8
	v_lshlrev_b32_e32 v8, 5, v64
	v_cndmask_b32_e32 v9, v194, v198, vcc
	v_lshlrev_b32_e32 v12, 2, v9
	v_or_b32_e32 v9, 8, v64
	v_add_u32_e32 v29, 0, v5
	v_add_u32_e32 v15, s24, v8
	v_lshlrev_b32_e32 v5, 5, v9
	v_lshlrev_b32_e32 v8, 4, v9
	v_lshlrev_b32_e32 v34, 5, v10
	v_lshlrev_b32_e32 v35, 4, v10
	v_add_u32_e32 v10, s24, v5
	v_add_u32_e32 v9, v29, v8
	v_add_u32_e32 v8, s24, v34
	v_add_u32_e32 v5, v29, v35
	v_lshlrev_b32_e32 v28, 4, v64
	s_ashr_i32 s38, s20, 6
	s_lshr_b32 s19, s20, 31
	s_add_i32 s19, s38, s19
	s_ashr_i32 s37, s19, 1
	v_and_b32_e32 v200, 31, v2
	s_lshl_b32 s19, s37, 5
	v_add_u32_e32 v11, v29, v28
	v_bfe_u32 v201, v2, 5, 1
	v_lshlrev_b32_e32 v203, 4, v201
	s_add_i32 s21, s38, 3
	s_cmp_gt_u32 s21, 6
	s_waitcnt vmcnt(7)
	v_and_b32_e32 v37, 0xffff0000, v17
	v_and_b32_e32 v36, 0xffff0000, v16
	v_lshlrev_b32_e32 v35, 16, v17
	v_lshlrev_b32_e32 v34, 16, v16
	v_and_b32_e32 v41, 0xffff0000, v19
	v_and_b32_e32 v40, 0xffff0000, v18
	v_pk_mul_f32 v[16:17], v[36:37], v[36:37]
	v_lshlrev_b32_e32 v39, 16, v19
	v_lshlrev_b32_e32 v38, 16, v18
	v_pk_mul_f32 v[18:19], v[40:41], v[40:41]
	v_pk_fma_f32 v[16:17], v[34:35], v[34:35], v[16:17]
	v_pk_fma_f32 v[18:19], v[38:39], v[38:39], v[18:19]
	v_pk_add_f32 v[16:17], v[16:17], v[16:17] op_sel:[0,1] op_sel_hi:[1,0]
	s_waitcnt vmcnt(5)
	v_and_b32_e32 v49, 0xffff0000, v26
	v_and_b32_e32 v51, 0xffff0000, v24
	v_pk_add_f32 v[16:17], v[18:19], v[16:17]
	v_lshlrev_b32_e32 v46, 16, v27
	v_and_b32_e32 v47, 0xffff0000, v27
	v_lshlrev_b32_e32 v48, 16, v26
	v_and_b32_e32 v27, 0xffff0000, v25
	v_lshlrev_b32_e32 v50, 16, v24
	v_pk_add_f32 v[16:17], v[18:19], v[16:17] op_sel:[1,0] op_sel_hi:[0,1]
	v_mov_b32_e32 v18, v49
	v_mov_b32_e32 v19, v51
	v_lshlrev_b32_e32 v26, 16, v25
	v_mul_f32_e32 v54, v27, v27
	v_mov_b32_e32 v56, v48
	v_mov_b32_e32 v57, v50
	v_pk_mul_f32 v[18:19], v[18:19], v[18:19]
	v_pk_fma_f32 v[54:55], v[26:27], v[26:27], v[54:55] op_sel_hi:[1,1,0]
	v_pk_fma_f32 v[18:19], v[56:57], v[56:57], v[18:19]
	v_mul_f32_e32 v52, v47, v47
	v_pk_add_f32 v[54:55], v[18:19], v[54:55] op_sel:[1,0] op_sel_hi:[0,1]
	v_pk_fma_f32 v[52:53], v[46:47], v[46:47], v[52:53] op_sel_hi:[1,1,0]
	v_pk_add_f32 v[18:19], v[18:19], v[54:55]
	v_and_b32_e32 v43, 0xffff0000, v20
	v_and_b32_e32 v45, 0xffff0000, v21
	s_waitcnt vmcnt(4)
; template <int DH, int NCOMP>
; __device__ __forceinline__ void tile_store_norm(const u32x4 (&r)[4], LAS unsigned char* buf, const LAS float* gain, float scale, int tid) {
;     ...
;     for (int i = 0; i < 4; ++i) { const int c = (NCOMP == 2) ? (i >> 1) : 0;
;         const float a0 = bflo(r[i].x), a1 = bfhi(r[i].x), a2 = bflo(r[i].y), a3 = bfhi(r[i].y), a4 = bflo(r[i].z), a5 = bfhi(r[i].z), a6 = bflo(r[i].w), a7 = bfhi(r[i].w);
;         ss[c] += (a0 * a0 + a1 * a1) + (a2 * a2 + a3 * a3) + (a4 * a4 + a5 * a5) + (a6 * a6 + a7 * a7); }
; #pragma unroll
;     for (int c = 0; c < NCOMP; ++c) { ss[c] += __shfl_xor(ss[c], 1); ss[c] += __shfl_xor(ss[c], 2); ss[c] += __shfl_xor(ss[c], 4); ss[c] = frsq(ss[c] * (1.0f / DH) + NORM_EPS) * scale; }
; #pragma unroll
;     for (int i = 0; i < 4; ++i) { const int c = (NCOMP == 2) ? (i >> 1) : 0; const int chunk = (tid & 7) + 8 * i, dch = chunk % CPR; const float rn = ss[c];
;         const f32x4 g0 = *(const LAS f32x4*)(gain + dch * 8), g1 = *(const LAS f32x4*)(gain + dch * 8 + 4);
;         u32x4 w;
;         w.x = pk2(bflo(r[i].x) * rn * g0[0], bfhi(r[i].x) * rn * g0[1]); w.y = pk2(bflo(r[i].y) * rn * g0[2], bfhi(r[i].y) * rn * g0[3]);
;         w.z = pk2(bflo(r[i].z) * rn * g1[0], bfhi(r[i].z) * rn * g1[1]); w.w = pk2(bflo(r[i].w) * rn * g1[2], bfhi(r[i].w) * rn * g1[3]);
;         *(LAS u32x4*)(buf + ((tid >> 3) * NCOMP + c) * KST + dch * 16) = w; }
; }
; template <int DH, int NCOMP>
; __device__ __forceinline__ void tile_store_k(const u32x4 (&r)[4], LAS unsigned char* buf, int tid) {
;     constexpr int KST = DH * 2 + 16, CPR = DH / 8;
; #pragma unroll
;     for (int i = 0; i < 4; ++i) { const int c = (NCOMP == 2) ? (i >> 1) : 0; const int chunk = (tid & 7) + 8 * i, dch = chunk % CPR;
;         *(LAS u32x4*)(buf + ((tid >> 3) * NCOMP + c) * KST + dch * 16) = r[i]; }
; }
;     template <bool BG = false>
;     __device__ __forceinline__ void run(LAS unsigned char* lds, f32x16 (&O)[NCOMP][NBLK], BgConv* bg = nullptr) const {
;         int tid = threadIdx.x; asm volatile("" : "+v"(tid));
;         const int lane = tid & 63, wid = __builtin_amdgcn_readfirstlane(tid >> 6), r = lane & 31, h = lane >> 5;
;         const int kh = wid & 1, compA = (wid >> 1) % NCOMP, rbA = wid / (2 * NCOMP);
;         const int dvp = wid % NDV, rbB = wid / NDV;
;         const int b16 = (lane >> 4) & 1, q4 = (lane & 15) >> 2, p4 = lane & 3;
	v_pk_mov_b32 v[58:59], v[22:23], v[32:33] op_sel:[1,0]
	v_lshlrev_b32_e32 v61, 16, v32
	v_lshlrev_b32_e32 v32, 16, v33
	v_and_b32_e32 v33, 0xffff0000, v33
	v_pk_add_f32 v[18:19], v[52:53], v[18:19]
	v_lshlrev_b32_e32 v42, 16, v20
	v_lshlrev_b32_e32 v44, 16, v21
	v_mul_f32_e32 v20, v43, v43
	v_mul_f32_e32 v24, v45, v45
	v_lshlrev_b32_e32 v55, 16, v30
	v_and_b32_e32 v57, 0xffff0000, v30
	v_mul_f32_e32 v17, v33, v33
	v_mul_f32_e32 v19, v32, v32
	v_lshlrev_b32_e32 v30, 16, v31
	v_and_b32_e32 v31, 0xffff0000, v31
	v_pk_fma_f32 v[20:21], v[42:43], v[42:43], v[20:21] op_sel_hi:[1,1,0]
	v_pk_fma_f32 v[24:25], v[44:45], v[44:45], v[24:25] op_sel_hi:[1,1,0]
	v_and_b32_e32 v56, 0xffff0000, v22
	v_pk_add_f32 v[16:17], v[18:19], v[16:17]
	v_pk_mul_f32 v[18:19], v[30:31], v[30:31]
	v_lshlrev_b32_e32 v54, 16, v22
	v_lshlrev_b32_e32 v60, 16, v23
	v_and_b32_e32 v59, 0xffff0000, v59
	v_and_b32_e32 v58, 0xffff0000, v58
	v_pk_mul_f32 v[22:23], v[56:57], v[56:57]
	v_mov_b32_e32 v21, v18
	v_mov_b32_e32 v25, v19
	v_pk_fma_f32 v[22:23], v[54:55], v[54:55], v[22:23]
	v_pk_mul_f32 v[62:63], v[58:59], v[58:59]
	v_pk_add_f32 v[18:19], v[20:21], v[24:25]
	v_pk_fma_f32 v[62:63], v[60:61], v[60:61], v[62:63]
	v_pk_add_f32 v[18:19], v[22:23], v[18:19]
	v_mov_b32_e32 v52, v34
	v_pk_add_f32 v[18:19], v[62:63], v[18:19]
	v_mov_b32_e32 v53, v36
	v_pk_add_f32 v[16:17], v[16:17], v[18:19]
	v_or_b32_e32 v19, 24, v64
	v_add_f32_e32 v16, v16, v17
	ds_bpermute_b32 v18, v14, v16
	v_lshlrev_b32_e32 v17, 5, v19
	v_lshlrev_b32_e32 v19, 4, v19
	v_mov_b32_e32 v36, v35
	v_mov_b32_e32 v35, v40
	s_waitcnt lgkmcnt(0)
	v_add_f32_e32 v18, v16, v18
	ds_bpermute_b32 v20, v13, v18
	v_add_u32_e32 v16, v29, v19
	v_and_or_b32 v19, s19, 32, v200
	v_mad_u32_u24 v62, v19, s23, 0
	v_mov_b32_e32 v40, v39
	s_waitcnt lgkmcnt(0)
	v_add_f32_e32 v63, v18, v20
	ds_bpermute_b32 v64, v12, v63
	ds_read_b128 v[18:21], v15
	ds_read_b128 v[22:25], v15 offset:16
	v_add_u32_e32 v17, s24, v17
	s_waitcnt lgkmcnt(2)
	v_add_f32_e32 v34, v63, v64
	v_fmamk_f32 v34, v34, 0x3b800000, v199
	v_rsq_f32_e32 v63, v34
	v_mov_b32_e32 v34, v38
	v_mul_f32_e32 v38, 0x3db8aa3b, v63
	v_pk_mul_f32 v[50:51], v[38:39], v[50:51] op_sel_hi:[0,1]
	v_pk_mul_f32 v[26:27], v[38:39], v[26:27] op_sel_hi:[0,1]
	s_waitcnt lgkmcnt(1)
	v_pk_mul_f32 v[18:19], v[18:19], v[50:51]
	v_pk_mul_f32 v[20:21], v[20:21], v[26:27]
	v_cvt_pk_bf16_f32 v18, v18, v19
	v_cvt_pk_bf16_f32 v19, v20, v21
	v_pk_mul_f32 v[20:21], v[38:39], v[48:49] op_sel_hi:[0,1]
	s_waitcnt lgkmcnt(0)
	v_pk_mul_f32 v[20:21], v[22:23], v[20:21]
	v_pk_mul_f32 v[22:23], v[38:39], v[46:47] op_sel_hi:[0,1]
	v_pk_mul_f32 v[22:23], v[24:25], v[22:23]
	v_cvt_pk_bf16_f32 v20, v20, v21
	v_cvt_pk_bf16_f32 v21, v22, v23
	ds_write_b128 v11, v[18:21]
	ds_read_b128 v[18:21], v10
	ds_read_b128 v[22:25], v10 offset:16
	v_pk_mul_f32 v[46:47], v[38:39], v[52:53] op_sel_hi:[0,1]
	v_pk_mul_f32 v[36:37], v[38:39], v[36:37] op_sel_hi:[0,1]
	v_mov_b32_e32 v26, v54
	s_waitcnt lgkmcnt(1)
	v_pk_mul_f32 v[18:19], v[18:19], v[46:47]
	v_pk_mul_f32 v[20:21], v[20:21], v[36:37]
	v_cvt_pk_bf16_f32 v18, v18, v19
	v_cvt_pk_bf16_f32 v19, v20, v21
	v_pk_mul_f32 v[20:21], v[38:39], v[34:35] op_sel_hi:[0,1]
	s_waitcnt lgkmcnt(0)
	v_pk_mul_f32 v[20:21], v[22:23], v[20:21]
	v_pk_mul_f32 v[22:23], v[38:39], v[40:41] op_sel_hi:[0,1]
	v_pk_mul_f32 v[22:23], v[24:25], v[22:23]
	v_cvt_pk_bf16_f32 v20, v20, v21
	v_cvt_pk_bf16_f32 v21, v22, v23
	ds_write_b128 v9, v[18:21]
	ds_read_b128 v[18:21], v8
	ds_read_b128 v[22:25], v8 offset:16
	v_pk_mul_f32 v[36:37], v[38:39], v[42:43] op_sel_hi:[0,1]
	v_mov_b32_e32 v27, v56
	v_mov_b32_e32 v34, v60
	s_waitcnt lgkmcnt(1)
	v_pk_mul_f32 v[18:19], v[18:19], v[36:37]
	v_pk_mul_f32 v[36:37], v[38:39], v[44:45] op_sel_hi:[0,1]
	v_pk_mul_f32 v[20:21], v[20:21], v[36:37]
	v_mov_b32_e32 v35, v58
	v_cvt_pk_bf16_f32 v18, v18, v19
	v_cvt_pk_bf16_f32 v19, v20, v21
	v_pk_mul_f32 v[20:21], v[38:39], v[26:27] op_sel_hi:[0,1]
	s_waitcnt lgkmcnt(0)
	v_pk_mul_f32 v[20:21], v[22:23], v[20:21]
	v_pk_mul_f32 v[22:23], v[38:39], v[34:35] op_sel_hi:[0,1]
	v_pk_mul_f32 v[22:23], v[24:25], v[22:23]
	v_cvt_pk_bf16_f32 v20, v20, v21
	v_cvt_pk_bf16_f32 v21, v22, v23
	ds_write_b128 v5, v[18:21]
	ds_read_b128 v[18:21], v17
	ds_read_b128 v[22:25], v17 offset:16
	v_mov_b32_e32 v56, v55
	v_pk_mul_f32 v[26:27], v[38:39], v[56:57] op_sel_hi:[0,1]
	v_mov_b32_e32 v58, v61
	s_waitcnt lgkmcnt(1)
	v_pk_mul_f32 v[18:19], v[18:19], v[26:27]
	v_pk_mul_f32 v[26:27], v[38:39], v[30:31] op_sel_hi:[0,1]
	v_pk_mul_f32 v[20:21], v[20:21], v[26:27]
	v_cvt_pk_bf16_f32 v18, v18, v19
	v_cvt_pk_bf16_f32 v19, v20, v21
	v_pk_mul_f32 v[20:21], v[38:39], v[58:59] op_sel_hi:[0,1]
	s_waitcnt lgkmcnt(0)
	v_pk_mul_f32 v[20:21], v[22:23], v[20:21]
	v_pk_mul_f32 v[22:23], v[38:39], v[32:33] op_sel_hi:[0,1]
	v_pk_mul_f32 v[22:23], v[24:25], v[22:23]
	v_cvt_pk_bf16_f32 v20, v20, v21
	v_cvt_pk_bf16_f32 v21, v22, v23
	ds_write_b128 v16, v[18:21]
	v_add_u32_e32 v18, v62, v203
	s_waitcnt lgkmcnt(0)
	s_barrier
	s_cbranch_scc1 .LBB0_673
	ds_read_b128 v[142:145], v18
	ds_read_b128 v[138:141], v18 offset:32
	ds_read_b128 v[134:137], v18 offset:64
	ds_read_b128 v[130:133], v18 offset:96
	ds_read_b128 v[126:129], v18 offset:128
	ds_read_b128 v[122:125], v18 offset:160
	ds_read_b128 v[118:121], v18 offset:192
	ds_read_b128 v[114:117], v18 offset:224
	ds_read_b128 v[110:113], v18 offset:256
	ds_read_b128 v[106:109], v18 offset:288
	ds_read_b128 v[102:105], v18 offset:320
	ds_read_b128 v[98:101], v18 offset:352
	ds_read_b128 v[94:97], v18 offset:384
	ds_read_b128 v[90:93], v18 offset:416
	ds_read_b128 v[86:89], v18 offset:448
	ds_read_b128 v[82:85], v18 offset:480

;     template <bool BG = false>
;     __device__ __forceinline__ void run(LAS unsigned char* lds, f32x16 (&O)[NCOMP][NBLK], BgConv* bg = nullptr) const {
;     ...
;         u32x4 kreg[4], vreg[4];
;         tile_load(kreg, K, ldk, tid); tile_load(vreg, V, ldv, tid);
;         tile_store_k<DH, NCOMP>(kreg, kbuf, tid);
; #pragma unroll
;         for (int c = 0; c < NCOMP; ++c)
; #pragma unroll
;             for (int b = 0; b < NBLK; ++b)
; #pragma unroll
;                 for (int i = 0; i < 16; ++i) O[c][b][i] = 0.f;
;         float lsum = 0.f;
;         f32x4 bgv[4], bgg;
;         __syncthreads();
.LBB0_675:
	s_lshl_b32 s20, s3, 1
	s_and_b32 s39, s20, 0x600
	s_lshl_b32 s20, s18, 8
	s_ashr_i32 s21, s20, 31
	s_lshl_b64 s[20:21], s[20:21], 12
	s_add_u32 s18, s13, s20
	s_addc_u32 s41, s15, s21
	v_ashrrev_i32_e32 v5, 31, v4
	s_add_u32 s40, s18, s8
	s_addc_u32 s41, s41, 0
	v_lshlrev_b64 v[46:47], 12, v[4:5]
	v_lshl_add_u64 v[6:7], s[40:41], 0, v[46:47]
	v_lshl_add_u64 v[14:15], v[6:7], 0, v[162:163]
	s_waitcnt lgkmcnt(0)
	s_barrier
	global_load_dwordx4 v[78:81], v[14:15], off offset:2048
	global_load_dwordx4 v[74:77], v[14:15], off offset:2176
	global_load_dwordx4 v[70:73], v[14:15], off offset:2304
	global_load_dwordx4 v[66:69], v[14:15], off offset:2432
	v_lshrrev_b32_e32 v5, 2, v2
	v_mul_lo_u32 v206, v4, s27
	v_or_b32_e32 v4, s19, v200
	v_lshlrev_b32_e32 v48, 3, v201
	v_lshlrev_b32_e32 v6, 4, v2
	v_and_b32_e32 v49, 24, v3
	v_lshlrev_b32_e32 v3, 1, v2
	v_mul_lo_u32 v50, v4, s28
	v_and_or_b32 v51, v5, 3, v48
	v_lshl_add_u64 v[46:47], v[46:47], 0, s[20:21]
	s_and_b32 s20, s38, 1
	s_lshl_b32 s21, s37, 1
	v_and_b32_e32 v208, 0x70, v6
	v_and_b32_e32 v52, 32, v3
	v_add_u32_e32 v210, s29, v50
	v_mad_u32_u24 v50, v51, s27, 0
	v_or3_b32 v46, v46, s39, v28
	s_sub_i32 s21, s38, s21
	v_lshl_or_b32 v28, s20, 5, v200
	v_mov_b32_e32 v204, 0
	v_add_u32_e32 v209, v29, v208
	v_add_u32_e32 v29, 0, v208
	v_add_u32_e32 v48, v210, v48
	v_add3_u32 v49, v50, v49, v52
	s_lshl_b32 s38, s20, 6
	v_mad_u32_u24 v28, v28, s23, 0
	s_lshl_b32 s21, s21, 8
	s_mov_b64 s[18:19], 0
	v_mov_b32_e32 v2, 0
	v_mov_b32_e32 v18, 0
	v_mov_b32_e32 v3, v204
	v_mov_b32_e32 v4, v204
	v_mov_b32_e32 v5, v204
	v_mov_b32_e32 v6, v204
	v_mov_b32_e32 v7, v204
	v_mov_b32_e32 v8, v204
	v_mov_b32_e32 v9, v204
	v_mov_b32_e32 v10, v204
	v_mov_b32_e32 v11, v204
	v_mov_b32_e32 v12, v204
	v_mov_b32_e32 v13, v204
	v_mov_b32_e32 v14, v204
	v_mov_b32_e32 v15, v204
	v_mov_b32_e32 v16, v204
	v_mov_b32_e32 v17, v204
	v_mov_b32_e32 v19, v204
	v_mov_b32_e32 v20, v204
	v_mov_b32_e32 v21, v204
	v_mov_b32_e32 v22, v204
	v_mov_b32_e32 v23, v204
	v_mov_b32_e32 v24, v204
	v_mov_b32_e32 v25, v204
	v_mov_b32_e32 v26, v204
	v_mov_b32_e32 v27, v204
	v_add_u32_e32 v211, v29, v206
	v_lshl_add_u64 v[166:167], s[10:11], 0, v[46:47]
	v_add_u32_e32 v205, s38, v48
	v_add_u32_e32 v207, v28, v203
	v_add_u32_e32 v162, s21, v49
	v_mov_b32_e32 v28, v204
	v_mov_b32_e32 v29, v204
	v_mov_b32_e32 v46, v204
	v_mov_b32_e32 v47, v204
	v_mov_b32_e32 v48, v204
	v_mov_b32_e32 v49, v204
	v_mov_b32_e32 v50, 0
	v_mov_b32_e32 v51, v204
	v_mov_b32_e32 v52, v204
	v_mov_b32_e32 v53, v204
	v_mov_b32_e32 v54, v204
	v_mov_b32_e32 v55, v204
	v_mov_b32_e32 v56, v204
	s_waitcnt vmcnt(7)
	ds_write_b128 v209, v[212:215]
	s_waitcnt vmcnt(6)
	ds_write_b128 v209, v[216:219] offset:128
	s_waitcnt vmcnt(5)
	ds_write_b128 v209, v[220:223] offset:256
	s_waitcnt vmcnt(4)
	ds_write_b128 v209, v[224:227] offset:384
	v_mov_b32_e32 v30, v204
	v_mov_b32_e32 v31, v204
	v_mov_b32_e32 v32, v204
	v_mov_b32_e32 v33, v204
	v_mov_b32_e32 v34, 0
	v_mov_b32_e32 v35, v204
	v_mov_b32_e32 v36, v204
	v_mov_b32_e32 v37, v204
	v_mov_b32_e32 v38, v204
	v_mov_b32_e32 v39, v204
	v_mov_b32_e32 v40, v204
	v_mov_b32_e32 v41, v204
	v_mov_b32_e32 v42, v204
	v_mov_b32_e32 v43, v204
	v_mov_b32_e32 v44, v204
	v_mov_b32_e32 v45, v204
	v_mov_b32_e32 v57, v204
	v_mov_b32_e32 v58, v204
	v_mov_b32_e32 v59, v204
	v_mov_b32_e32 v60, v204
	v_mov_b32_e32 v61, v204
	v_mov_b32_e32 v62, v204
	v_mov_b32_e32 v63, v204
	v_mov_b32_e32 v64, v204
	v_mov_b32_e32 v65, v204
	s_waitcnt lgkmcnt(0)
	s_barrier

; #define LAS __attribute__((address_space(3)))
;     template <bool BG = false>
;     __device__ __forceinline__ void run(LAS unsigned char* lds, f32x16 (&O)[NCOMP][NBLK], BgConv* bg = nullptr) const {
;         int tid = threadIdx.x; asm volatile("" : "+v"(tid));
;         const int lane = tid & 63, wid = __builtin_amdgcn_readfirstlane(tid >> 6), r = lane & 31, h = lane >> 5;
;         const int kh = wid & 1, compA = (wid >> 1) % NCOMP, rbA = wid / (2 * NCOMP);
;         const int dvp = wid % NDV, rbB = wid / NDV;
;         const int b16 = (lane >> 4) & 1, q4 = (lane & 15) >> 2, p4 = lane & 3;
;         LAS unsigned char* kbuf = lds + AT_K; LAS unsigned char* vbuf = lds + AT_V; LAS unsigned char* pbuf = lds + AT_P;
;         LAS float* gq = (LAS float*)(lds + AT_G); LAS float* lbuf = (LAS float*)(lds + AT_L);
;         if (tid < DH) gq[tid] = qg[tid];
;         __syncthreads();
;         bf16x8 qf[KS];
;         const float qscale = ((DH == 128) ? 0.08838834764831845f : 0.0625f) * LOG2E;
; #pragma unroll
;         for (int pass = 0; pass < NRB / 2; ++pass) {
;             u32x4 qr[4]; tile_load(qr, Q + (size_t)(64 * pass) * ldq, ldq, tid);
;             tile_store_norm<DH, NCOMP>(qr, kbuf, gq, qscale, tid);
;             __syncthreads();
;             if (rbA / 2 == pass) {
; #pragma unroll
;                 for (int s = 0; s < KS; ++s) qf[s] = *(const LAS bf16x8*)(kbuf + ((32 * (rbA & 1) + r) * NCOMP + compA) * KST + (16 * s + 8 * h) * 2);
;             }
;             __syncthreads();
;         }
;         u32x4 kreg[4], vreg[4];
;         tile_load(kreg, K, ldk, tid); tile_load(vreg, V, ldv, tid);
; template <bool BG = false>
; __device__ __forceinline__ void diff_unit(Frame& F, int bh, int c, BgConv* bg = nullptr) {
;     ...
;     AU u; u.Q = Z + (size_t)(b * SEQ + 64 * c) * NZ + ZQ_DIFF + hd * 256; u.ldq = NZ; u.K = Z + (size_t)(b * SEQ) * NZ + ZK_DIFF + hd * 256; u.ldk = NZ;
;     u.V = Z + (size_t)(b * SEQ) * NZ + ZV_DIFF + hd * 256; u.ldv = NZ; u.ntiles = c + 1; u.qg = F.in[8]; u.m2 = sc[1];
.LBB0_725:
	s_or_b64 exec, exec, s[24:25]
	s_ashr_i32 s16, s72, 5
	s_and_b32 s73, s72, 31
	s_xor_b32 s83, s73, 63
	s_lshl_b32 s24, s16, 10
	s_and_b32 s76, s24, 0xfffff000
	s_lshl_b32 s24, s83, 6
	s_or_b32 s25, s76, s24
	s_mul_i32 s27, s25, 0x3c00
	s_mul_hi_i32 s24, s25, 0x3c00
	s_add_u32 s27, s3, s27
	s_addc_u32 s29, s12, s24
	s_lshl_b32 s16, s16, 8
	s_and_b32 s16, s16, 0x300
	s_lshl_b32 s24, s16, 1
	s_add_u32 s28, s27, s24
	v_ashrrev_i32_e32 v175, 3, v4
	v_lshlrev_b32_e32 v2, 3, v4
	s_addc_u32 s29, s29, 0
	v_and_b32_e32 v2, 56, v2
	v_mad_i64_i32 v[8:9], s[36:37], v175, s46, 0
	v_lshl_add_u64 v[6:7], v[8:9], 1, s[28:29]
	v_lshlrev_b32_e32 v2, 1, v2
	v_lshl_add_u64 v[6:7], v[6:7], 0, v[2:3]
	v_add_co_u32_e32 v10, vcc, s47, v6
	s_waitcnt lgkmcnt(0)
	s_nop 0
	v_addc_co_u32_e32 v11, vcc, 0, v7, vcc
	v_lshl_add_u64 v[6:7], v[6:7], 0, s[20:21]
	s_barrier
	global_load_dwordx4 v[10:13], v[10:11], off offset:2048
	v_cmp_lt_i32_e32 vcc, v159, v162
	global_load_dwordx4 v[14:17], v[6:7], off offset:128
	v_ashrrev_i32_e32 v47, 2, v4
	v_cndmask_b32_e32 v5, v157, v159, vcc
	v_cmp_lt_i32_e32 vcc, v163, v162
	v_lshlrev_b32_e32 v169, 2, v5
	v_and_b32_e32 v46, 7, v4
	v_cndmask_b32_e32 v18, v157, v163, vcc
	v_cmp_lt_i32_e32 vcc, v164, v162
	v_lshlrev_b32_e32 v168, 2, v18
	v_and_b32_e32 v5, 0xffffffe, v47
	v_cndmask_b32_e32 v19, v157, v164, vcc
	v_lshlrev_b32_e32 v167, 2, v19
	global_load_dwordx4 v[18:21], v[6:7], off offset:256
	global_load_dwordx4 v[22:25], v[6:7], off offset:384
	s_mul_i32 s98, s76, 0x3c00
	s_mul_hi_i32 s99, s76, 0x3c00
	s_add_u32 s98, s3, s98
	s_addc_u32 s99, s12, s99
	s_add_u32 s98, s98, s24
	s_addc_u32 s99, s99, 0
	s_add_u32 s100, s98, 0x2800
	s_addc_u32 s101, s99, 0
	s_add_u32 s98, s98, 0x2000
	s_addc_u32 s99, s99, 0
	v_lshlrev_b64 v[148:149], 1, v[8:9]
	v_lshl_add_u64 v[150:151], s[98:99], 0, v[148:149]
	v_lshl_add_u64 v[148:149], s[100:101], 0, v[148:149]
	v_lshl_add_u64 v[150:151], v[150:151], 0, v[2:3]
	v_lshl_add_u64 v[148:149], v[148:149], 0, v[2:3]
	global_load_dwordx4 v[132:135], v[150:151], off
	global_load_dwordx4 v[136:139], v[150:151], off offset:128
	global_load_dwordx4 v[140:143], v[150:151], off offset:256
	global_load_dwordx4 v[144:147], v[150:151], off offset:384
	global_load_dwordx4 v[128:131], v[148:149], off
	global_load_dwordx4 v[124:127], v[148:149], off offset:128
	global_load_dwordx4 v[120:123], v[148:149], off offset:256
	global_load_dwordx4 v[116:119], v[148:149], off offset:384
	v_mul_lo_u32 v5, v5, s45
	s_add_i32 s77, 0, 0x16000
	v_lshl_add_u32 v54, v46, 5, s77
	v_add_u32_e32 v5, 0, v5
	s_ashr_i32 s16, s26, 6
	s_ashr_i32 s27, s26, 7
	s_lshr_b32 s26, s26, 31
	s_lshr_b32 s28, s16, 30
	s_add_i32 s26, s27, s26
	s_add_i32 s28, s16, s28
	s_and_b32 s26, s26, -2
	s_ashr_i32 s81, s28, 2
	v_bfe_u32 v176, v4, 5, 1
	s_sub_i32 s79, s27, s26
	s_add_i32 s26, s81, 1
	s_lshl_b32 s86, s81, 5
	v_and_b32_e32 v171, 31, v4
	s_cmp_gt_u32 s26, 2
	v_lshlrev_b32_e32 v172, 4, v176
	s_waitcnt vmcnt(11)
	v_and_b32_e32 v27, 0xffff0000, v13
	v_and_b32_e32 v29, 0xffff0000, v12
	s_waitcnt vmcnt(10)
	v_and_b32_e32 v35, 0xffff0000, v17
	v_and_b32_e32 v37, 0xffff0000, v16
	v_lshlrev_b32_e32 v26, 16, v13
	v_lshlrev_b32_e32 v28, 16, v12
	v_lshlrev_b32_e32 v30, 16, v11
	v_and_b32_e32 v31, 0xffff0000, v11
	v_lshlrev_b32_e32 v32, 16, v10
	v_and_b32_e32 v33, 0xffff0000, v10
	v_lshlrev_b32_e32 v34, 16, v17
	v_lshlrev_b32_e32 v36, 16, v16
	v_lshlrev_b32_e32 v38, 16, v15
	v_and_b32_e32 v39, 0xffff0000, v15
	v_lshlrev_b32_e32 v40, 16, v14
	v_and_b32_e32 v41, 0xffff0000, v14
	v_mov_b32_e32 v10, v27
	v_mov_b32_e32 v11, v35
	v_mov_b32_e32 v14, v29
	v_mov_b32_e32 v15, v37
	v_mov_b32_e32 v6, v26
	v_mov_b32_e32 v7, v34
	v_mov_b32_e32 v12, v28
	v_mov_b32_e32 v13, v36
	v_pk_mul_f32 v[10:11], v[10:11], v[10:11]
	v_pk_mul_f32 v[14:15], v[14:15], v[14:15]
	v_mov_b32_e32 v42, v31
	v_mov_b32_e32 v43, v39
	v_pk_fma_f32 v[6:7], v[6:7], v[6:7], v[10:11]
	v_pk_fma_f32 v[10:11], v[12:13], v[12:13], v[14:15]
	v_mov_b32_e32 v14, v33
	v_mov_b32_e32 v15, v41
	v_mov_b32_e32 v16, v30
	v_mov_b32_e32 v17, v38
	v_mov_b32_e32 v44, v32
	v_mov_b32_e32 v45, v40
	v_pk_mul_f32 v[42:43], v[42:43], v[42:43]
	v_pk_mul_f32 v[14:15], v[14:15], v[14:15]
	v_pk_fma_f32 v[12:13], v[16:17], v[16:17], v[42:43]
	v_pk_fma_f32 v[14:15], v[44:45], v[44:45], v[14:15]
	s_nop 0
	v_pk_add_f32 v[12:13], v[14:15], v[12:13]
	ds_read_b128 v[14:17], v54 offset:16
	v_pk_add_f32 v[10:11], v[10:11], v[12:13]
	v_or_b32_e32 v12, 1, v47
	v_pk_add_f32 v[6:7], v[6:7], v[10:11]
	v_or_b32_e32 v11, 8, v46
	v_add_f32_e32 v7, v6, v7
	ds_bpermute_b32 v10, v169, v7
	v_lshl_add_u32 v55, v11, 5, s77
	v_lshlrev_b32_e32 v11, 4, v11
	v_add_u32_e32 v56, v5, v11
	v_lshlrev_b32_e32 v6, 4, v46
	s_waitcnt lgkmcnt(0)
	v_add_f32_e32 v7, v7, v10
	ds_bpermute_b32 v10, v168, v7
	v_add_u32_e32 v43, v5, v6
	s_waitcnt lgkmcnt(0)
	v_add_f32_e32 v10, v7, v10
	ds_bpermute_b32 v13, v167, v10
	v_mul_lo_u32 v7, v12, s45
	v_add_u32_e32 v7, 0, v7
	v_add_u32_e32 v58, v7, v11
	v_add_u32_e32 v57, v7, v6
	s_waitcnt lgkmcnt(0)
	v_add_f32_e32 v10, v10, v13
	v_fmamk_f32 v10, v10, 0x3c000000, v165
	v_rsq_f32_e32 v42, v10
	ds_read_b128 v[10:13], v54
	v_mul_f32_e32 v42, 0x3e0293ee, v42
	v_pk_mul_f32 v[32:33], v[42:43], v[32:33] op_sel_hi:[0,1]
	v_pk_mul_f32 v[30:31], v[42:43], v[30:31] op_sel_hi:[0,1]
	s_waitcnt lgkmcnt(0)
	v_pk_mul_f32 v[10:11], v[10:11], v[32:33]
	v_pk_mul_f32 v[12:13], v[12:13], v[30:31]
	v_cvt_pk_bf16_f32 v10, v10, v11
	v_cvt_pk_bf16_f32 v11, v12, v13
	v_pk_mul_f32 v[12:13], v[42:43], v[28:29] op_sel_hi:[0,1]
	s_waitcnt vmcnt(9)
; template <int DH, int NCOMP>
; __device__ __forceinline__ void tile_store_norm(const u32x4 (&r)[4], LAS unsigned char* buf, const LAS float* gain, float scale, int tid) {
;     ...
;     for (int i = 0; i < 4; ++i) { const int c = (NCOMP == 2) ? (i >> 1) : 0;
;         const float a0 = bflo(r[i].x), a1 = bfhi(r[i].x), a2 = bflo(r[i].y), a3 = bfhi(r[i].y), a4 = bflo(r[i].z), a5 = bfhi(r[i].z), a6 = bflo(r[i].w), a7 = bfhi(r[i].w);
;         ss[c] += (a0 * a0 + a1 * a1) + (a2 * a2 + a3 * a3) + (a4 * a4 + a5 * a5) + (a6 * a6 + a7 * a7); }
; #pragma unroll
;     for (int c = 0; c < NCOMP; ++c) { ss[c] += __shfl_xor(ss[c], 1); ss[c] += __shfl_xor(ss[c], 2); ss[c] += __shfl_xor(ss[c], 4); ss[c] = frsq(ss[c] * (1.0f / DH) + NORM_EPS) * scale; }
; #pragma unroll
;     for (int i = 0; i < 4; ++i) { const int c = (NCOMP == 2) ? (i >> 1) : 0; const int chunk = (tid & 7) + 8 * i, dch = chunk % CPR; const float rn = ss[c];
;         const f32x4 g0 = *(const LAS f32x4*)(gain + dch * 8), g1 = *(const LAS f32x4*)(gain + dch * 8 + 4);
;         u32x4 w;
;         w.x = pk2(bflo(r[i].x) * rn * g0[0], bfhi(r[i].x) * rn * g0[1]); w.y = pk2(bflo(r[i].y) * rn * g0[2], bfhi(r[i].y) * rn * g0[3]);
;         w.z = pk2(bflo(r[i].z) * rn * g1[0], bfhi(r[i].z) * rn * g1[1]); w.w = pk2(bflo(r[i].w) * rn * g1[2], bfhi(r[i].w) * rn * g1[3]);
;         *(LAS u32x4*)(buf + ((tid >> 3) * NCOMP + c) * KST + dch * 16) = w; }
; }
; template <int DH, int NCOMP>
; __device__ __forceinline__ void tile_store_k(const u32x4 (&r)[4], LAS unsigned char* buf, int tid) {
;     constexpr int KST = DH * 2 + 16, CPR = DH / 8;
; #pragma unroll
;     for (int i = 0; i < 4; ++i) { const int c = (NCOMP == 2) ? (i >> 1) : 0; const int chunk = (tid & 7) + 8 * i, dch = chunk % CPR;
;         *(LAS u32x4*)(buf + ((tid >> 3) * NCOMP + c) * KST + dch * 16) = r[i]; }
; }
;     template <bool BG = false>
;     __device__ __forceinline__ void run(LAS unsigned char* lds, f32x16 (&O)[NCOMP][NBLK], BgConv* bg = nullptr) const {
;         int tid = threadIdx.x; asm volatile("" : "+v"(tid));
;         const int lane = tid & 63, wid = __builtin_amdgcn_readfirstlane(tid >> 6), r = lane & 31, h = lane >> 5;
;         const int kh = wid & 1, compA = (wid >> 1) % NCOMP, rbA = wid / (2 * NCOMP);
;         const int dvp = wid % NDV, rbB = wid / NDV;
;         const int b16 = (lane >> 4) & 1, q4 = (lane & 15) >> 2, p4 = lane & 3;
	v_lshlrev_b32_e32 v28, 16, v21
	v_and_b32_e32 v29, 0xffff0000, v21
	v_lshlrev_b32_e32 v30, 16, v20
	v_and_b32_e32 v31, 0xffff0000, v20
	v_lshlrev_b32_e32 v20, 16, v19
	v_and_b32_e32 v21, 0xffff0000, v19
	s_waitcnt vmcnt(8)
	v_and_b32_e32 v19, 0xffff0000, v25
	v_lshlrev_b32_e32 v32, 16, v18
	v_and_b32_e32 v33, 0xffff0000, v18
	v_lshlrev_b32_e32 v18, 16, v25
	v_mov_b32_e32 v44, v29
	v_mov_b32_e32 v45, v19
	v_pk_mul_f32 v[12:13], v[14:15], v[12:13]
	v_pk_mul_f32 v[14:15], v[42:43], v[26:27] op_sel_hi:[0,1]
	v_pk_mul_f32 v[26:27], v[42:43], v[40:41] op_sel_hi:[0,1]
	v_mov_b32_e32 v40, v28
	v_mov_b32_e32 v41, v18
	v_pk_mul_f32 v[44:45], v[44:45], v[44:45]
	v_mov_b32_e32 v46, v31
	v_pk_fma_f32 v[40:41], v[40:41], v[40:41], v[44:45]
	v_and_b32_e32 v45, 0xffff0000, v24
	v_lshlrev_b32_e32 v44, 16, v24
	v_mov_b32_e32 v47, v45
	v_mov_b32_e32 v24, v30
	v_mov_b32_e32 v25, v44
	v_pk_mul_f32 v[46:47], v[46:47], v[46:47]
	v_mov_b32_e32 v50, v21
	v_pk_fma_f32 v[24:25], v[24:25], v[24:25], v[46:47]
	v_and_b32_e32 v47, 0xffff0000, v23
	v_lshlrev_b32_e32 v46, 16, v23
	v_mov_b32_e32 v51, v47
	v_mov_b32_e32 v48, v20
	v_mov_b32_e32 v49, v46
	v_pk_mul_f32 v[50:51], v[50:51], v[50:51]
	v_mov_b32_e32 v52, v33
	v_pk_fma_f32 v[48:49], v[48:49], v[48:49], v[50:51]
	v_and_b32_e32 v51, 0xffff0000, v22
	v_lshlrev_b32_e32 v50, 16, v22
	v_mov_b32_e32 v53, v51
	v_mov_b32_e32 v22, v32
	v_mov_b32_e32 v23, v50
	v_pk_mul_f32 v[52:53], v[52:53], v[52:53]
	v_pk_mul_f32 v[14:15], v[16:17], v[14:15]
	v_pk_fma_f32 v[22:23], v[22:23], v[22:23], v[52:53]
	v_cvt_pk_bf16_f32 v12, v12, v13
	v_pk_add_f32 v[22:23], v[22:23], v[48:49]
	v_cvt_pk_bf16_f32 v13, v14, v15
	v_pk_add_f32 v[22:23], v[24:25], v[22:23]
	ds_write_b128 v43, v[10:13]
	v_pk_add_f32 v[22:23], v[40:41], v[22:23]
	ds_read_b128 v[10:13], v55
	ds_read_b128 v[14:17], v55 offset:16
	v_add_f32_e32 v24, v22, v23
	ds_bpermute_b32 v25, v169, v24
	v_pk_mul_f32 v[22:23], v[42:43], v[38:39] op_sel_hi:[0,1]
	s_waitcnt lgkmcnt(2)
	v_pk_mul_f32 v[12:13], v[12:13], v[22:23]
	v_pk_mul_f32 v[10:11], v[10:11], v[26:27]
	s_waitcnt lgkmcnt(0)
	v_add_f32_e32 v22, v24, v25
	ds_bpermute_b32 v23, v168, v22
	v_cvt_pk_bf16_f32 v10, v10, v11
	v_cvt_pk_bf16_f32 v11, v12, v13
	v_pk_mul_f32 v[12:13], v[42:43], v[36:37] op_sel_hi:[0,1]
	v_pk_mul_f32 v[12:13], v[14:15], v[12:13]
	s_waitcnt lgkmcnt(0)
	v_add_f32_e32 v22, v22, v23
	ds_bpermute_b32 v23, v167, v22
	v_pk_mul_f32 v[14:15], v[42:43], v[34:35] op_sel_hi:[0,1]
	v_pk_mul_f32 v[14:15], v[16:17], v[14:15]
	v_cvt_pk_bf16_f32 v12, v12, v13
	v_cvt_pk_bf16_f32 v13, v14, v15
	ds_write_b128 v56, v[10:13]
	s_waitcnt lgkmcnt(1)
	v_add_f32_e32 v10, v22, v23
	v_fmamk_f32 v10, v10, 0x3c000000, v165
	v_rsq_f32_e32 v22, v10
	ds_read_b128 v[10:13], v54
	ds_read_b128 v[14:17], v54 offset:16
	v_mul_f32_e32 v22, 0x3e0293ee, v22
	v_pk_mul_f32 v[24:25], v[22:23], v[32:33] op_sel_hi:[0,1]
	v_pk_mul_f32 v[20:21], v[22:23], v[20:21] op_sel_hi:[0,1]
	s_waitcnt lgkmcnt(1)
	v_pk_mul_f32 v[10:11], v[10:11], v[24:25]
	v_pk_mul_f32 v[12:13], v[12:13], v[20:21]
	v_cvt_pk_bf16_f32 v10, v10, v11
	v_cvt_pk_bf16_f32 v11, v12, v13
	v_pk_mul_f32 v[12:13], v[22:23], v[30:31] op_sel_hi:[0,1]
	s_waitcnt lgkmcnt(0)
	v_pk_mul_f32 v[12:13], v[14:15], v[12:13]
	v_pk_mul_f32 v[14:15], v[22:23], v[28:29] op_sel_hi:[0,1]
	v_pk_mul_f32 v[14:15], v[16:17], v[14:15]
	v_cvt_pk_bf16_f32 v12, v12, v13
	v_cvt_pk_bf16_f32 v13, v14, v15
	ds_write_b128 v57, v[10:13]
	ds_read_b128 v[10:13], v55
	ds_read_b128 v[14:17], v55 offset:16
	v_pk_mul_f32 v[20:21], v[22:23], v[50:51] op_sel_hi:[0,1]
	s_waitcnt lgkmcnt(1)
	v_pk_mul_f32 v[10:11], v[10:11], v[20:21]
	v_pk_mul_f32 v[20:21], v[22:23], v[46:47] op_sel_hi:[0,1]
	v_pk_mul_f32 v[12:13], v[12:13], v[20:21]
	v_cvt_pk_bf16_f32 v10, v10, v11
	v_cvt_pk_bf16_f32 v11, v12, v13
	v_pk_mul_f32 v[12:13], v[22:23], v[44:45] op_sel_hi:[0,1]
	s_waitcnt lgkmcnt(0)
	v_pk_mul_f32 v[12:13], v[12:13], v[14:15]
	v_pk_mul_f32 v[14:15], v[22:23], v[18:19] op_sel_hi:[0,1]
	v_pk_mul_f32 v[14:15], v[14:15], v[16:17]
	v_cvt_pk_bf16_f32 v12, v12, v13
	v_cvt_pk_bf16_f32 v13, v14, v15
	ds_write_b128 v58, v[10:13]
	s_waitcnt lgkmcnt(0)
	s_barrier
	s_cbranch_scc1 .LBB0_727
	v_and_or_b32 v10, s86, 32, v171
	v_lshl_add_u32 v10, v10, 1, s79
	v_mul_i32_i24_e32 v10, 0x110, v10
	v_add3_u32 v10, 0, v10, v172
	ds_read_b128 v[112:115], v10
	ds_read_b128 v[108:111], v10 offset:32
	ds_read_b128 v[104:107], v10 offset:64
	ds_read_b128 v[100:103], v10 offset:96
	ds_read_b128 v[96:99], v10 offset:128
	ds_read_b128 v[92:95], v10 offset:160
	ds_read_b128 v[88:91], v10 offset:192
	ds_read_b128 v[84:87], v10 offset:224
.LBB0_727:
	s_mul_i32 s75, s76, 0x3c00
	s_mul_hi_i32 s74, s76, 0x3c00
	s_add_u32 s26, s3, s75
	s_addc_u32 s27, s12, s74
	s_add_u32 s26, s26, s24
	s_addc_u32 s27, s27, 0
	s_add_u32 s28, s26, 0x2000
	s_addc_u32 s29, s27, 0
	s_add_u32 s26, s26, 0x2800
	s_addc_u32 s27, s27, 0
	v_lshlrev_b64 v[24:25], 1, v[8:9]
	v_lshl_add_u64 v[8:9], s[28:29], 0, v[24:25]
	v_lshl_add_u64 v[24:25], s[26:27], 0, v[24:25]
	v_lshl_add_u64 v[152:153], v[8:9], 0, v[2:3]
	v_lshl_add_u64 v[154:155], v[24:25], 0, v[2:3]
	s_waitcnt lgkmcnt(0)
	s_barrier
	v_lshlrev_b32_e32 v2, 4, v4
	v_and_b32_e32 v179, 0x70, v2
	v_add_u32_e32 v182, v5, v179
	v_add_u32_e32 v183, v7, v179
	s_cmpk_gt_i32 s80, 0x57ff
	s_mov_b32 s89, 0
	s_waitcnt vmcnt(7)
	ds_write_b128 v182, v[132:135]
	s_waitcnt vmcnt(6)
	ds_write_b128 v182, v[136:139] offset:128
	s_waitcnt vmcnt(5)
	ds_write_b128 v183, v[140:143]
	s_waitcnt vmcnt(4)
	ds_write_b128 v183, v[144:147] offset:128
	s_waitcnt lgkmcnt(0)
	s_barrier
	s_cbranch_scc1 .LBB0_729
	s_sub_i32 s37, 0x57ff, s80
	s_mul_hi_u32 s84, s37, s40
	s_mul_i32 s85, s84, s38
	s_sub_i32 s37, s37, s85
	s_lshr_b32 s36, s83, 1
	s_add_i32 s85, s84, 1
	s_sub_i32 s87, s37, s38
	s_cmp_ge_u32 s37, s38
	s_cselect_b32 s84, s85, s84
	s_cselect_b32 s37, s87, s37
	s_add_i32 s85, s84, 1
	s_cmp_ge_u32 s37, s38
	s_cselect_b32 s37, s85, s84
	s_xor_b32 s37, s37, s39
	s_sub_i32 s37, s37, s39
	s_add_i32 s37, s37, 1
	s_min_i32 s89, s37, s36

; #define LAS __attribute__((address_space(3)))
;     template <bool BG = false>
;     __device__ __forceinline__ void run(LAS unsigned char* lds, f32x16 (&O)[NCOMP][NBLK], BgConv* bg = nullptr) const {
;         int tid = threadIdx.x; asm volatile("" : "+v"(tid));
;         const int lane = tid & 63, wid = __builtin_amdgcn_readfirstlane(tid >> 6), r = lane & 31, h = lane >> 5;
;         const int kh = wid & 1, compA = (wid >> 1) % NCOMP, rbA = wid / (2 * NCOMP);
;         const int dvp = wid % NDV, rbB = wid / NDV;
;         const int b16 = (lane >> 4) & 1, q4 = (lane & 15) >> 2, p4 = lane & 3;
;         LAS unsigned char* kbuf = lds + AT_K; LAS unsigned char* vbuf = lds + AT_V; LAS unsigned char* pbuf = lds + AT_P;
;         LAS float* gq = (LAS float*)(lds + AT_G); LAS float* lbuf = (LAS float*)(lds + AT_L);
;         if (tid < DH) gq[tid] = qg[tid];
;         __syncthreads();
;         bf16x8 qf[KS];
;         const float qscale = ((DH == 128) ? 0.08838834764831845f : 0.0625f) * LOG2E;
; #pragma unroll
;         for (int pass = 0; pass < NRB / 2; ++pass) {
;             u32x4 qr[4]; tile_load(qr, Q + (size_t)(64 * pass) * ldq, ldq, tid);
;             tile_store_norm<DH, NCOMP>(qr, kbuf, gq, qscale, tid);
;             __syncthreads();
;             if (rbA / 2 == pass) {
; #pragma unroll
;                 for (int s = 0; s < KS; ++s) qf[s] = *(const LAS bf16x8*)(kbuf + ((32 * (rbA & 1) + r) * NCOMP + compA) * KST + (16 * s + 8 * h) * 2);
;             }
;             __syncthreads();
;         }
;         u32x4 kreg[4], vreg[4];
;         tile_load(kreg, K, ldk, tid); tile_load(vreg, V, ldv, tid);
; template <bool BG = false>
; __device__ __forceinline__ void diff_unit(Frame& F, int bh, int c, BgConv* bg = nullptr) {
;     ...
;     AU u; u.Q = Z + (size_t)(b * SEQ + 64 * c) * NZ + ZQ_DIFF + hd * 256; u.ldq = NZ; u.K = Z + (size_t)(b * SEQ) * NZ + ZK_DIFF + hd * 256; u.ldk = NZ;
;     u.V = Z + (size_t)(b * SEQ) * NZ + ZV_DIFF + hd * 256; u.ldv = NZ; u.ntiles = c + 1; u.qg = F.in[8]; u.m2 = sc[1];
.LBB0_753:
	s_or_b64 exec, exec, s[36:37]
	s_lshl_b32 s16, s73, 6
	s_or_b32 s25, s76, s16
	s_mul_i32 s36, s25, 0x3c00
	s_mul_hi_i32 s16, s25, 0x3c00
	s_add_u32 s36, s3, s36
	s_addc_u32 s16, s12, s16
	s_add_u32 s36, s36, s24
	v_ashrrev_i32_e32 v176, 3, v4
	v_lshlrev_b32_e32 v2, 3, v4
	s_addc_u32 s37, s16, 0
	v_and_b32_e32 v2, 56, v2
	v_mad_i64_i32 v[8:9], s[84:85], v176, s46, 0
	v_lshl_add_u64 v[6:7], v[8:9], 1, s[36:37]
	v_lshlrev_b32_e32 v2, 1, v2
	v_lshl_add_u64 v[6:7], v[6:7], 0, v[2:3]
	v_add_co_u32_e32 v10, vcc, s47, v6
	v_lshl_add_u64 v[30:31], v[6:7], 0, s[20:21]
	s_nop 0
	v_addc_co_u32_e32 v11, vcc, 0, v7, vcc
	s_waitcnt lgkmcnt(0)
	s_barrier
	global_load_dwordx4 v[10:13], v[10:11], off offset:2048
	v_ashrrev_i32_e32 v7, 2, v4
	global_load_dwordx4 v[14:17], v[30:31], off offset:128
	v_and_b32_e32 v5, 7, v4
	v_and_b32_e32 v18, 0xffffffe, v7
	v_lshl_add_u32 v58, v5, 5, s77
	v_lshlrev_b32_e32 v6, 4, v5
	v_or_b32_e32 v5, 8, v5
	v_mul_lo_u32 v26, v18, s45
	v_lshl_add_u32 v59, v5, 5, s77
	v_lshlrev_b32_e32 v60, 4, v5
	ds_read_b128 v[18:21], v58
	ds_read_b128 v[22:25], v58 offset:16
	v_add_u32_e32 v5, 0, v26
	global_load_dwordx4 v[26:29], v[30:31], off offset:256
	s_nop 0
	global_load_dwordx4 v[30:33], v[30:31], off offset:384
	v_lshlrev_b64 v[148:149], 1, v[8:9]
	v_lshl_add_u64 v[150:151], s[28:29], 0, v[148:149]
	v_lshl_add_u64 v[148:149], s[26:27], 0, v[148:149]
	v_lshl_add_u64 v[150:151], v[150:151], 0, v[2:3]
	v_lshl_add_u64 v[148:149], v[148:149], 0, v[2:3]
	global_load_dwordx4 v[132:135], v[150:151], off
	global_load_dwordx4 v[136:139], v[150:151], off offset:128
	global_load_dwordx4 v[140:143], v[150:151], off offset:256
	global_load_dwordx4 v[144:147], v[150:151], off offset:384
	global_load_dwordx4 v[128:131], v[148:149], off
	global_load_dwordx4 v[124:127], v[148:149], off offset:128
	global_load_dwordx4 v[120:123], v[148:149], off offset:256
	global_load_dwordx4 v[116:119], v[148:149], off offset:384
	v_or_b32_e32 v7, 1, v7
	v_mul_lo_u32 v7, v7, s45
	v_add_u32_e32 v7, 0, v7
	s_ashr_i32 s16, s79, 6
	s_ashr_i32 s36, s79, 7
	s_lshr_b32 s37, s79, 31
	s_add_i32 s37, s36, s37
	s_lshr_b32 s76, s16, 30
	s_and_b32 s37, s37, -2
	s_add_i32 s76, s16, s76
	s_sub_i32 s36, s36, s37
	s_ashr_i32 s37, s76, 2
	v_bfe_u32 v179, v4, 5, 1
	s_add_i32 s77, s37, 1
	s_lshl_b32 s76, s37, 5
	v_and_b32_e32 v171, 31, v4
	s_cmp_gt_u32 s77, 2
	v_lshlrev_b32_e32 v173, 4, v179
	s_waitcnt vmcnt(11)
	v_lshlrev_b32_e32 v34, 16, v13
	v_and_b32_e32 v35, 0xffff0000, v13
	v_and_b32_e32 v37, 0xffff0000, v12
	v_and_b32_e32 v13, 0xffff0000, v11
	v_and_b32_e32 v39, 0xffff0000, v10
	s_waitcnt vmcnt(10)
	v_and_b32_e32 v41, 0xffff0000, v17
	v_and_b32_e32 v43, 0xffff0000, v16
	v_and_b32_e32 v45, 0xffff0000, v15
	v_and_b32_e32 v47, 0xffff0000, v14
	v_lshlrev_b32_e32 v36, 16, v12
	v_lshlrev_b32_e32 v12, 16, v11
	v_lshlrev_b32_e32 v38, 16, v10
	v_lshlrev_b32_e32 v40, 16, v17
	v_lshlrev_b32_e32 v42, 16, v16
	v_lshlrev_b32_e32 v44, 16, v15
	v_lshlrev_b32_e32 v46, 16, v14
	v_mov_b32_e32 v14, v35
	v_mov_b32_e32 v15, v41
	v_mov_b32_e32 v48, v37
	v_mov_b32_e32 v49, v43
	v_mov_b32_e32 v52, v13
	v_mov_b32_e32 v53, v45
	v_mov_b32_e32 v56, v39
	v_mov_b32_e32 v57, v47
	v_mov_b32_e32 v10, v34
	v_mov_b32_e32 v11, v40
	v_mov_b32_e32 v16, v36
	v_mov_b32_e32 v17, v42
	v_mov_b32_e32 v50, v12
	v_mov_b32_e32 v51, v44
	v_mov_b32_e32 v54, v38
	v_mov_b32_e32 v55, v46
	v_pk_mul_f32 v[14:15], v[14:15], v[14:15]
	v_pk_mul_f32 v[48:49], v[48:49], v[48:49]
	v_pk_mul_f32 v[52:53], v[52:53], v[52:53]
	v_pk_mul_f32 v[56:57], v[56:57], v[56:57]
	v_pk_fma_f32 v[10:11], v[10:11], v[10:11], v[14:15]
	v_pk_fma_f32 v[14:15], v[16:17], v[16:17], v[48:49]
	v_pk_fma_f32 v[16:17], v[50:51], v[50:51], v[52:53]
	v_pk_fma_f32 v[48:49], v[54:55], v[54:55], v[56:57]
	v_add_u32_e32 v54, v5, v60
	v_pk_add_f32 v[16:17], v[48:49], v[16:17]
	v_add_u32_e32 v49, v5, v6
	v_pk_add_f32 v[14:15], v[14:15], v[16:17]
	v_add_u32_e32 v55, v7, v6
	v_pk_add_f32 v[10:11], v[10:11], v[14:15]
	v_add_u32_e32 v56, v7, v60
	v_add_f32_e32 v10, v10, v11
	ds_bpermute_b32 v11, v169, v10
	s_waitcnt lgkmcnt(0)
	v_add_f32_e32 v10, v10, v11
	ds_bpermute_b32 v11, v168, v10
	s_waitcnt lgkmcnt(0)
	v_add_f32_e32 v10, v10, v11
	ds_bpermute_b32 v11, v167, v10
	s_waitcnt lgkmcnt(0)
	v_add_f32_e32 v10, v10, v11
	v_fmamk_f32 v10, v10, 0x3c000000, v165
	v_rsq_f32_e32 v10, v10
	s_nop 0
	v_mul_f32_e32 v48, 0x3e0293ee, v10
	v_pk_mul_f32 v[12:13], v[48:49], v[12:13] op_sel_hi:[0,1]
	v_pk_mul_f32 v[16:17], v[48:49], v[34:35] op_sel_hi:[0,1]
	v_pk_mul_f32 v[14:15], v[48:49], v[36:37] op_sel_hi:[0,1]
	v_pk_mul_f32 v[12:13], v[20:21], v[12:13]
	v_pk_mul_f32 v[16:17], v[24:25], v[16:17]
	s_waitcnt vmcnt(9)
	v_and_b32_e32 v21, 0xffff0000, v29
	v_lshlrev_b32_e32 v24, 16, v27
	v_and_b32_e32 v25, 0xffff0000, v27
	s_waitcnt vmcnt(8)
; template <int DH, int NCOMP>
; __device__ __forceinline__ void tile_store_norm(const u32x4 (&r)[4], LAS unsigned char* buf, const LAS float* gain, float scale, int tid) {
;     ...
;     for (int i = 0; i < 4; ++i) { const int c = (NCOMP == 2) ? (i >> 1) : 0;
;         const float a0 = bflo(r[i].x), a1 = bfhi(r[i].x), a2 = bflo(r[i].y), a3 = bfhi(r[i].y), a4 = bflo(r[i].z), a5 = bfhi(r[i].z), a6 = bflo(r[i].w), a7 = bfhi(r[i].w);
;         ss[c] += (a0 * a0 + a1 * a1) + (a2 * a2 + a3 * a3) + (a4 * a4 + a5 * a5) + (a6 * a6 + a7 * a7); }
; #pragma unroll
;     for (int c = 0; c < NCOMP; ++c) { ss[c] += __shfl_xor(ss[c], 1); ss[c] += __shfl_xor(ss[c], 2); ss[c] += __shfl_xor(ss[c], 4); ss[c] = frsq(ss[c] * (1.0f / DH) + NORM_EPS) * scale; }
; #pragma unroll
;     for (int i = 0; i < 4; ++i) { const int c = (NCOMP == 2) ? (i >> 1) : 0; const int chunk = (tid & 7) + 8 * i, dch = chunk % CPR; const float rn = ss[c];
;         const f32x4 g0 = *(const LAS f32x4*)(gain + dch * 8), g1 = *(const LAS f32x4*)(gain + dch * 8 + 4);
;         u32x4 w;
;         w.x = pk2(bflo(r[i].x) * rn * g0[0], bfhi(r[i].x) * rn * g0[1]); w.y = pk2(bflo(r[i].y) * rn * g0[2], bfhi(r[i].y) * rn * g0[3]);
;         w.z = pk2(bflo(r[i].z) * rn * g1[0], bfhi(r[i].z) * rn * g1[1]); w.w = pk2(bflo(r[i].w) * rn * g1[2], bfhi(r[i].w) * rn * g1[3]);
;         *(LAS u32x4*)(buf + ((tid >> 3) * NCOMP + c) * KST + dch * 16) = w; }
; }
; template <int DH, int NCOMP>
; __device__ __forceinline__ void tile_store_k(const u32x4 (&r)[4], LAS unsigned char* buf, int tid) {
;     constexpr int KST = DH * 2 + 16, CPR = DH / 8;
; #pragma unroll
;     for (int i = 0; i < 4; ++i) { const int c = (NCOMP == 2) ? (i >> 1) : 0; const int chunk = (tid & 7) + 8 * i, dch = chunk % CPR;
;         *(LAS u32x4*)(buf + ((tid >> 3) * NCOMP + c) * KST + dch * 16) = r[i]; }
; }
;     template <bool BG = false>
;     __device__ __forceinline__ void run(LAS unsigned char* lds, f32x16 (&O)[NCOMP][NBLK], BgConv* bg = nullptr) const {
;         int tid = threadIdx.x; asm volatile("" : "+v"(tid));
;         const int lane = tid & 63, wid = __builtin_amdgcn_readfirstlane(tid >> 6), r = lane & 31, h = lane >> 5;
;         const int kh = wid & 1, compA = (wid >> 1) % NCOMP, rbA = wid / (2 * NCOMP);
;         const int dvp = wid % NDV, rbB = wid / NDV;
;         const int b16 = (lane >> 4) & 1, q4 = (lane & 15) >> 2, p4 = lane & 3;
	v_and_b32_e32 v27, 0xffff0000, v33
	v_pk_mul_f32 v[14:15], v[22:23], v[14:15]
	v_lshlrev_b32_e32 v20, 16, v29
	v_lshlrev_b32_e32 v22, 16, v28
	v_and_b32_e32 v23, 0xffff0000, v28
	v_lshlrev_b32_e32 v28, 16, v26
	v_and_b32_e32 v29, 0xffff0000, v26
	v_lshlrev_b32_e32 v26, 16, v33
	v_mov_b32_e32 v36, v21
	v_mov_b32_e32 v37, v27
	v_mov_b32_e32 v34, v20
	v_mov_b32_e32 v35, v26
	v_pk_mul_f32 v[36:37], v[36:37], v[36:37]
	v_pk_mul_f32 v[10:11], v[48:49], v[38:39] op_sel_hi:[0,1]
	v_pk_fma_f32 v[34:35], v[34:35], v[34:35], v[36:37]
	v_and_b32_e32 v37, 0xffff0000, v32
	v_lshlrev_b32_e32 v36, 16, v32
	v_mov_b32_e32 v38, v23
	v_mov_b32_e32 v39, v37
	v_mov_b32_e32 v32, v22
	v_mov_b32_e32 v33, v36
	v_pk_mul_f32 v[38:39], v[38:39], v[38:39]
	v_mov_b32_e32 v50, v25
	v_pk_fma_f32 v[32:33], v[32:33], v[32:33], v[38:39]
	v_and_b32_e32 v39, 0xffff0000, v31
	v_lshlrev_b32_e32 v38, 16, v31
	v_mov_b32_e32 v51, v39
	v_pk_mul_f32 v[10:11], v[18:19], v[10:11]
	v_pk_mul_f32 v[18:19], v[48:49], v[46:47] op_sel_hi:[0,1]
	v_mov_b32_e32 v46, v24
	v_mov_b32_e32 v47, v38
	v_pk_mul_f32 v[50:51], v[50:51], v[50:51]
	v_mov_b32_e32 v52, v29
	v_pk_fma_f32 v[46:47], v[46:47], v[46:47], v[50:51]
	v_and_b32_e32 v51, 0xffff0000, v30
	v_lshlrev_b32_e32 v50, 16, v30
	v_mov_b32_e32 v53, v51
	v_mov_b32_e32 v30, v28
	v_mov_b32_e32 v31, v50
	v_pk_mul_f32 v[52:53], v[52:53], v[52:53]
	v_cvt_pk_bf16_f32 v10, v10, v11
	v_pk_fma_f32 v[30:31], v[30:31], v[30:31], v[52:53]
	v_cvt_pk_bf16_f32 v11, v12, v13
	v_pk_add_f32 v[30:31], v[30:31], v[46:47]
	v_cvt_pk_bf16_f32 v12, v14, v15
	v_pk_add_f32 v[30:31], v[32:33], v[30:31]
	v_cvt_pk_bf16_f32 v13, v16, v17
	v_pk_add_f32 v[30:31], v[34:35], v[30:31]
	ds_write_b128 v49, v[10:13]
	v_add_f32_e32 v30, v30, v31
	ds_read_b128 v[10:13], v59
	ds_read_b128 v[14:17], v59 offset:16
	ds_bpermute_b32 v31, v169, v30
	s_waitcnt lgkmcnt(2)
	v_pk_mul_f32 v[10:11], v[10:11], v[18:19]
	v_pk_mul_f32 v[18:19], v[48:49], v[44:45] op_sel_hi:[0,1]
	v_pk_mul_f32 v[12:13], v[12:13], v[18:19]
	s_waitcnt lgkmcnt(0)
	v_add_f32_e32 v18, v30, v31
	ds_bpermute_b32 v19, v168, v18
	v_cvt_pk_bf16_f32 v10, v10, v11
	v_cvt_pk_bf16_f32 v11, v12, v13
	v_pk_mul_f32 v[12:13], v[48:49], v[42:43] op_sel_hi:[0,1]
	v_pk_mul_f32 v[12:13], v[14:15], v[12:13]
	s_waitcnt lgkmcnt(0)
	v_add_f32_e32 v18, v18, v19
	ds_bpermute_b32 v19, v167, v18
	v_pk_mul_f32 v[14:15], v[48:49], v[40:41] op_sel_hi:[0,1]
	v_pk_mul_f32 v[14:15], v[16:17], v[14:15]
	v_cvt_pk_bf16_f32 v12, v12, v13
	v_cvt_pk_bf16_f32 v13, v14, v15
	ds_write_b128 v54, v[10:13]
	s_waitcnt lgkmcnt(1)
	v_add_f32_e32 v10, v18, v19
	v_fmamk_f32 v10, v10, 0x3c000000, v165
	v_rsq_f32_e32 v18, v10
	ds_read_b128 v[10:13], v58
	ds_read_b128 v[14:17], v58 offset:16
	v_mul_f32_e32 v18, 0x3e0293ee, v18
	v_pk_mul_f32 v[28:29], v[18:19], v[28:29] op_sel_hi:[0,1]
	v_pk_mul_f32 v[24:25], v[18:19], v[24:25] op_sel_hi:[0,1]
	s_waitcnt lgkmcnt(1)
	v_pk_mul_f32 v[10:11], v[10:11], v[28:29]
	v_pk_mul_f32 v[12:13], v[12:13], v[24:25]
	v_cvt_pk_bf16_f32 v10, v10, v11
	v_cvt_pk_bf16_f32 v11, v12, v13
	v_pk_mul_f32 v[12:13], v[18:19], v[22:23] op_sel_hi:[0,1]
	s_waitcnt lgkmcnt(0)
	v_pk_mul_f32 v[12:13], v[14:15], v[12:13]
	v_pk_mul_f32 v[14:15], v[18:19], v[20:21] op_sel_hi:[0,1]
	v_pk_mul_f32 v[14:15], v[16:17], v[14:15]
	v_cvt_pk_bf16_f32 v12, v12, v13
	v_cvt_pk_bf16_f32 v13, v14, v15
	ds_write_b128 v55, v[10:13]
	ds_read_b128 v[10:13], v59
	ds_read_b128 v[14:17], v59 offset:16
	v_pk_mul_f32 v[20:21], v[18:19], v[50:51] op_sel_hi:[0,1]
	s_waitcnt lgkmcnt(1)
	v_pk_mul_f32 v[10:11], v[10:11], v[20:21]
	v_pk_mul_f32 v[20:21], v[18:19], v[38:39] op_sel_hi:[0,1]
	v_pk_mul_f32 v[12:13], v[12:13], v[20:21]
	v_cvt_pk_bf16_f32 v10, v10, v11
	v_cvt_pk_bf16_f32 v11, v12, v13
	v_pk_mul_f32 v[12:13], v[18:19], v[36:37] op_sel_hi:[0,1]
	s_waitcnt lgkmcnt(0)
	v_pk_mul_f32 v[12:13], v[12:13], v[14:15]
	v_pk_mul_f32 v[14:15], v[18:19], v[26:27] op_sel_hi:[0,1]
	v_pk_mul_f32 v[14:15], v[14:15], v[16:17]
	v_cvt_pk_bf16_f32 v12, v12, v13
	v_cvt_pk_bf16_f32 v13, v14, v15
	ds_write_b128 v56, v[10:13]
	s_waitcnt lgkmcnt(0)
	s_barrier
	s_cbranch_scc1 .LBB0_755
	v_and_or_b32 v10, s76, 32, v171
	v_lshl_add_u32 v10, v10, 1, s36
	v_mul_i32_i24_e32 v10, 0x110, v10
	v_add3_u32 v10, 0, v10, v173
	ds_read_b128 v[112:115], v10
	ds_read_b128 v[108:111], v10 offset:32
	ds_read_b128 v[104:107], v10 offset:64
	ds_read_b128 v[100:103], v10 offset:96
	ds_read_b128 v[96:99], v10 offset:128
	ds_read_b128 v[92:95], v10 offset:160
	ds_read_b128 v[88:91], v10 offset:192
	ds_read_b128 v[84:87], v10 offset:224
.LBB0_755:
	v_lshlrev_b64 v[24:25], 1, v[8:9]
	v_lshl_add_u64 v[8:9], s[28:29], 0, v[24:25]
	v_lshl_add_u64 v[24:25], s[26:27], 0, v[24:25]
	v_lshl_add_u64 v[152:153], v[8:9], 0, v[2:3]
	v_lshl_add_u64 v[154:155], v[24:25], 0, v[2:3]
	s_waitcnt lgkmcnt(0)
	s_barrier
	v_lshlrev_b32_e32 v2, 4, v4
	v_and_b32_e32 v180, 0x70, v2
	s_cmpk_gt_i32 s80, 0x57ff
	v_add_u32_e32 v183, v5, v180
	v_add_u32_e32 v184, v7, v180
	s_mov_b32 s79, 0
	s_waitcnt vmcnt(7)
	ds_write_b128 v183, v[132:135]
	s_waitcnt vmcnt(6)
	ds_write_b128 v183, v[136:139] offset:128
	s_waitcnt vmcnt(5)
	ds_write_b128 v184, v[140:143]
	s_waitcnt vmcnt(4)
	ds_write_b128 v184, v[144:147] offset:128
	s_waitcnt lgkmcnt(0)
	s_barrier
	s_cbranch_scc1 .LBB0_757
	s_sub_i32 s27, 0x57ff, s80
	s_mul_hi_u32 s28, s27, s40
	s_mul_i32 s29, s28, s38
	s_sub_i32 s27, s27, s29
	s_lshr_b32 s26, s73, 1
	s_add_i32 s29, s28, 1
	s_sub_i32 s77, s27, s38
	s_cmp_ge_u32 s27, s38
	s_cselect_b32 s28, s29, s28
	s_cselect_b32 s27, s77, s27
	s_add_i32 s29, s28, 1
	s_cmp_ge_u32 s27, s38
	s_cselect_b32 s27, s29, s28
	s_xor_b32 s27, s27, s39
	s_sub_i32 s27, s27, s39
	s_add_i32 s27, s27, 1
	s_min_i32 s79, s27, s26
